# phase 3 transposing stage (SGU U^T, scan K^T/V^T): lane->(row,chunk) remap so 4 adjacent lanes read one contiguous 64B row segment
# speedup vs baseline: 1.0120x; 1.0114x over previous
.LBB0_279:
	s_andn2_b64 vcc, exec, s[4:5]
	s_cbranch_vccnz .LBB0_384
	v_bfe_u32 v24, v191, 2, 6
	v_and_b32_e32 v25, 3, v191
	v_lshl_or_b32 v24, v25, 6, v24
	v_and_b32_e32 v25, 0x100, v191
	v_or_b32_e32 v24, v24, v25
	v_add_u32_e32 v25, 0x200, v24
	v_add_u32_e32 v26, 0x400, v24
	v_add_u32_e32 v27, 0x600, v24
	v_lshlrev_b32_e32 v28, 1, v24
	v_readlane_b32 s0, v254, 59
	s_lshl_b32 s4, s0, 11
	s_ashr_i32 s5, s4, 31
	s_lshl_b64 s[4:5], s[4:5], 2
	s_add_u32 s20, s38, s4
	s_addc_u32 s21, s39, s5
	v_readlane_b32 s4, v252, 12
	v_readlane_b32 s10, v252, 18
	s_cmp_lg_u32 s0, 0
	v_readlane_b32 s0, v252, 11
	v_readlane_b32 s5, v252, 13
	v_readlane_b32 s9, v252, 17
	v_readlane_b32 s10, v254, 58
	s_cselect_b32 s96, s0, 0
	v_ashrrev_i32_e32 v2, 7, v191
	v_cmp_eq_u32_e64 s[4:5], 0, v192
	s_lshl_b32 s9, s10, 4
	v_ashrrev_i32_e32 v3, 31, v2
	v_writelane_b32 v255, s4, 50
	s_bitcmp0_b32 s96, 0
	v_lshlrev_b64 v[2:3], 16, v[2:3]
	v_readlane_b32 s12, v252, 20
	v_readlane_b32 s13, v252, 21
	v_writelane_b32 v255, s5, 51
	s_cselect_b64 s[4:5], -1, 0
	v_and_b32_e32 v68, 15, v191
	v_and_b32_e32 v4, 0xffffff80, v191
	v_lshl_add_u64 v[64:65], s[12:13], 0, v[2:3]
	v_writelane_b32 v255, s4, 10
	v_lshlrev_b32_e32 v2, 3, v68
	v_ashrrev_i32_e32 v3, 4, v191
	v_ashrrev_i32_e32 v5, 31, v4
	v_readlane_b32 s14, v252, 22
	v_readlane_b32 s15, v252, 23
	v_writelane_b32 v255, s5, 11
	v_cmp_gt_i32_e64 s[4:5], v2, v3
	v_lshl_add_u64 v[66:67], v[4:5], 2, s[14:15]
	v_or_b32_e32 v4, 4, v2
	v_writelane_b32 v255, s4, 12
	v_or_b32_e32 v5, 5, v2
	v_or_b32_e32 v6, 2, v2
	v_writelane_b32 v255, s5, 13
	v_cmp_gt_i32_e64 s[4:5], v4, v3
	v_or_b32_e32 v7, 6, v2
	v_or_b32_e32 v9, 3, v2
	v_writelane_b32 v255, s4, 14
	v_or_b32_e32 v10, 7, v2
	v_add_u32_e32 v12, 0x200, v191
	v_writelane_b32 v255, s5, 15
	v_cmp_lt_i32_e64 s[4:5], v2, v3
	v_readlane_b32 s6, v252, 14
	v_readlane_b32 s7, v252, 15
	v_writelane_b32 v255, s4, 16
	v_lshlrev_b32_e32 v72, 7, v3
	v_lshlrev_b32_e32 v152, 5, v68
	v_writelane_b32 v255, s5, 17
	v_cmp_gt_i32_e64 s[4:5], v5, v3
	v_lshl_add_u64 v[70:71], s[12:13], 0, v[152:153]
	v_add_u32_e32 v15, 0x600, v191
	v_writelane_b32 v255, s4, 18
	v_ashrrev_i32_e32 v16, 4, v15
	v_readlane_b32 s16, v252, 24
	v_writelane_b32 v255, s5, 19
	v_cmp_gt_i32_e64 s[4:5], v6, v3
	v_readlane_b32 s17, v252, 25
	v_readlane_b32 s18, v252, 26
	v_writelane_b32 v255, s4, 20
	v_readlane_b32 s19, v252, 27
	v_cmp_lt_i32_e64 s[18:19], v2, v16
	v_writelane_b32 v255, s5, 21
	v_cmp_gt_i32_e64 s[4:5], v7, v3
	v_cmp_gt_i32_e64 s[90:91], v4, v16
	s_movk_i32 s0, 0x2800
	v_writelane_b32 v255, s4, 22
	v_lshlrev_b32_e32 v78, 7, v16
	v_lshlrev_b32_e32 v0, 1, v191
	v_writelane_b32 v255, s5, 23
	v_cmp_gt_i32_e64 s[4:5], v9, v3
	v_and_b32_e32 v19, 48, v191
	v_or_b32_e32 v98, 0x70, v192
	v_writelane_b32 v255, s4, 24
	v_ashrrev_i32_e32 v1, 31, v0
	v_lshl_add_u32 v8, v68, 4, 0
	v_writelane_b32 v255, s5, 25
	v_cmp_gt_i32_e64 s[4:5], v10, v3
	v_add_u32_e32 v103, 0, v19
	v_or_b32_e32 v96, 48, v192
	v_writelane_b32 v255, s4, 26
	v_mul_u32_u24_e32 v21, 0x110, v98
	v_lshlrev_b32_e32 v23, 7, v68
	v_writelane_b32 v255, s5, 27
	s_movk_i32 s5, 0x110
	v_mul_lo_u32 v11, v3, s5
	v_ashrrev_i32_e32 v3, 4, v12
	v_cmp_gt_i32_e64 s[6:7], v2, v3
	v_cmp_gt_i32_e64 s[12:13], v5, v3
	v_lshlrev_b32_e32 v74, 7, v3
	v_writelane_b32 v255, s6, 28
	v_cmp_gt_i32_e64 s[14:15], v4, v3
	s_waitcnt lgkmcnt(0)
	v_mul_lo_u32 v13, v3, s5
	v_writelane_b32 v255, s7, 29
	v_writelane_b32 v255, s12, 30
	v_cmp_lt_i32_e64 s[6:7], v2, v3
	s_movk_i32 s4, 0x880
	v_writelane_b32 v255, s13, 31
	v_cmp_gt_i32_e64 s[12:13], v6, v3
	v_ashrrev_i32_e32 v73, 31, v72
	v_ashrrev_i32_e32 v75, 31, v74
	v_writelane_b32 v255, s12, 32
	v_ashrrev_i32_e32 v79, 31, v78
	v_mul_u32_u24_e32 v105, 0x110, v68
	v_writelane_b32 v255, s13, 33
	v_cmp_gt_i32_e64 s[12:13], v7, v3
	v_mul_u32_u24_e32 v107, 0x110, v96
	v_or_b32_e32 v100, 16, v68
	v_writelane_b32 v254, s12, 59
	v_or_b32_e32 v102, 32, v68
	v_or_b32_e32 v104, 64, v68
	v_writelane_b32 v254, s13, 60
	v_cmp_gt_i32_e64 s[12:13], v9, v3
	v_or_b32_e32 v106, 0x50, v68
	v_or_b32_e32 v108, 0x60, v68
	v_writelane_b32 v254, s12, 61
	v_lshlrev_b64 v[128:129], 1, v[0:1]
	v_add_u32_e32 v165, v8, v11
	v_writelane_b32 v254, s13, 62
	v_cmp_gt_i32_e64 s[12:13], v10, v3
	v_add_u32_e32 v3, 0x400, v191
	v_ashrrev_i32_e32 v14, 4, v3
	v_writelane_b32 v255, s12, 0
	v_cmp_lt_i32_e64 s[16:17], v2, v14
	v_cmp_gt_i32_e64 s[22:23], v4, v14
	v_writelane_b32 v255, s13, 1
	v_cmp_gt_i32_e64 s[12:13], v2, v14
	v_lshlrev_b32_e32 v76, 7, v14
	v_ashrrev_i32_e32 v77, 31, v76
	v_writelane_b32 v255, s12, 2
	v_add_u32_e32 v166, v8, v13
	v_add_u32_e32 v172, v103, v21
	v_writelane_b32 v255, s13, 3
	v_cmp_gt_i32_e64 s[12:13], v5, v14
	v_lshlrev_b32_e32 v173, 1, v23
	v_readlane_b32 s8, v252, 16
	v_writelane_b32 v255, s12, 4
	v_readlane_b32 s11, v252, 19
	s_nop 0
	v_writelane_b32 v255, s13, 5
	v_cmp_gt_i32_e64 s[12:13], v6, v14
	s_nop 1
	v_writelane_b32 v255, s12, 6
	s_nop 1
	v_writelane_b32 v255, s13, 7
	v_cmp_gt_i32_e64 s[12:13], v7, v14
	s_nop 1
	v_writelane_b32 v255, s12, 8
	s_nop 1
	v_writelane_b32 v255, s13, 9
	v_cmp_gt_i32_e64 s[12:13], v9, v14
	s_nop 1
	v_writelane_b32 v255, s12, 34
	s_nop 1
	v_writelane_b32 v255, s13, 35
	v_cmp_gt_i32_e64 s[12:13], v10, v14
	v_mul_lo_u32 v14, v14, s5
	v_add_u32_e32 v167, v8, v14
	v_writelane_b32 v255, s12, 36
	s_nop 1
	v_writelane_b32 v255, s13, 37
	v_cmp_gt_i32_e64 s[12:13], v2, v16
	v_ashrrev_i32_e32 v2, 31, v24
	v_lshrrev_b32_e32 v2, 26, v2
	v_writelane_b32 v255, s12, 38
	v_add_u32_e32 v2, v24, v2
	s_nop 0
	v_writelane_b32 v255, s13, 39
	v_cmp_gt_i32_e64 s[12:13], v5, v16
	s_nop 1
	v_writelane_b32 v255, s12, 40
	s_nop 1
	v_writelane_b32 v255, s13, 41
	v_cmp_gt_i32_e64 s[12:13], v6, v16
	v_ashrrev_i32_e32 v6, 6, v2
	v_and_b32_e32 v2, 0xffffffc0, v2
	v_writelane_b32 v255, s12, 42
	v_sub_u32_e32 v4, v24, v2
	v_mul_lo_u32 v2, v6, s4
	v_writelane_b32 v255, s13, 43
	v_cmp_gt_i32_e64 s[12:13], v7, v16
	v_add_u32_e32 v69, 0, v2
	v_ashrrev_i32_e32 v2, 31, v25
	v_writelane_b32 v255, s12, 44
	v_lshrrev_b32_e32 v2, 26, v2
	v_add_u32_e32 v2, v25, v2
	v_writelane_b32 v255, s13, 45
	v_cmp_gt_i32_e64 s[12:13], v9, v16
	v_mul_lo_u32 v9, v16, s5
	v_mul_lo_u32 v80, v4, s0
	v_writelane_b32 v255, s12, 46
	v_lshlrev_b32_e32 v97, 2, v4
	v_lshlrev_b32_e32 v4, 1, v4
	v_writelane_b32 v255, s13, 47
	v_cmp_gt_i32_e64 s[12:13], v10, v16
	v_ashrrev_i32_e32 v10, 6, v2
	v_and_b32_e32 v2, 0xffffffc0, v2
	v_sub_u32_e32 v5, v25, v2
	v_mul_lo_u32 v2, v10, s4
	v_add_u32_e32 v99, 0, v2
	v_ashrrev_i32_e32 v2, 31, v26
	v_lshrrev_b32_e32 v2, 26, v2
	v_add_u32_e32 v2, v26, v2
	v_ashrrev_i32_e32 v7, 6, v2
	v_and_b32_e32 v2, 0xffffffc0, v2
	v_sub_u32_e32 v2, v26, v2
	v_mul_lo_u32 v88, v2, s0
	v_lshlrev_b32_e32 v17, 2, v2
	v_ashrrev_i32_e32 v2, 31, v27
	v_lshrrev_b32_e32 v2, 26, v2
	v_mul_lo_u32 v3, v7, s4
	v_add_u32_e32 v2, v27, v2
	v_add_u32_e32 v16, 0, v3
	v_ashrrev_i32_e32 v3, 6, v2
	v_and_b32_e32 v2, 0xffffffc0, v2
	v_sub_u32_e32 v2, v27, v2
	v_mul_lo_u32 v84, v5, s0
	v_mul_lo_u32 v92, v2, s0
	s_lshl_b32 s0, s10, 5
	v_lshlrev_b32_e32 v18, 2, v2
	v_or_b32_e32 v2, s0, v68
	v_mul_lo_u32 v2, v2, s5
	v_add_u32_e32 v20, 0, v2
	v_lshrrev_b32_e32 v2, 2, v191
	v_lshlrev_b32_e32 v90, 3, v7
	v_and_b32_e32 v7, 12, v2
	v_or_b32_e32 v2, s0, v7
	v_or_b32_e32 v110, s9, v7
	v_sub_u32_e32 v7, 0x7f, v4
	v_or_b32_e32 v4, 1, v4
	v_sub_u32_e32 v4, 0x7f, v4
	v_cvt_f32_i32_e32 v162, v4
	v_lshlrev_b32_e32 v4, 1, v5
	v_lshlrev_b32_e32 v101, 2, v5
	v_sub_u32_e32 v5, 0x7f, v4
	v_or_b32_e32 v4, 1, v4
	v_sub_u32_e32 v4, 0x7f, v4
	v_cvt_f32_i32_e32 v164, v4
	v_or_b32_e32 v4, s9, v68
	v_mul_lo_u32 v4, v4, s5
	v_add_u32_e32 v22, 0, v4
	v_or_b32_e32 v4, 1, v110
	v_cvt_f32_u32_e32 v163, v5
	v_ashrrev_i32_e32 v5, 31, v4
	v_lshlrev_b64 v[114:115], 10, v[4:5]
	v_or_b32_e32 v4, 2, v110
	v_ashrrev_i32_e32 v5, 31, v4
	v_lshlrev_b64 v[116:117], 10, v[4:5]
	v_or_b32_e32 v4, 3, v110
	v_ashrrev_i32_e32 v5, 31, v4
	v_lshlrev_b64 v[118:119], 10, v[4:5]
	v_lshlrev_b32_e32 v4, 7, v6
	v_sub_u32_e32 v4, v28, v4
	v_lshlrev_b32_e32 v82, 3, v6
	v_or_b32_e32 v4, 1, v4
	s_movk_i32 s0, 0x1400
	v_ashrrev_i32_e32 v83, 31, v82
	v_mul_lo_u32 v4, v4, s0
	v_cvt_f32_u32_e32 v109, v7
	v_ashrrev_i32_e32 v5, 31, v4
	v_lshlrev_b64 v[6:7], 1, v[82:83]
	v_lshl_add_u64 v[120:121], v[4:5], 1, v[6:7]
	v_lshlrev_b32_e32 v4, 1, v25
	v_lshlrev_b32_e32 v5, 7, v10
	v_sub_u32_e32 v4, v4, v5
	v_lshlrev_b32_e32 v86, 3, v10
	v_or_b32_e32 v4, 1, v4
	v_ashrrev_i32_e32 v81, 31, v80
	v_ashrrev_i32_e32 v87, 31, v86
	v_lshlrev_b32_e32 v94, 3, v3
	v_mul_lo_u32 v3, v3, s4
	v_mul_lo_u32 v4, v4, s0
	v_writelane_b32 v255, s12, 48
	v_ashrrev_i32_e32 v85, 31, v84
	v_add_u32_e32 v15, 0, v3
	v_ashrrev_i32_e32 v3, 31, v2
	s_cmp_lt_u32 s96, 2
	v_ashrrev_i32_e32 v111, 31, v110
	v_lshl_add_u64 v[122:123], v[80:81], 1, v[6:7]
	v_ashrrev_i32_e32 v5, 31, v4
	v_lshlrev_b64 v[6:7], 1, v[86:87]
	v_writelane_b32 v255, s13, 49
	v_ashrrev_i32_e32 v89, 31, v88
	v_ashrrev_i32_e32 v91, 31, v90
	v_ashrrev_i32_e32 v93, 31, v92
	v_ashrrev_i32_e32 v95, 31, v94
	s_cselect_b64 s[24:25], -1, 0
	v_lshlrev_b64 v[112:113], 10, v[110:111]
	v_lshl_add_u64 v[124:125], v[4:5], 1, v[6:7]
	v_lshl_add_u64 v[126:127], v[84:85], 1, v[6:7]
	v_add_u32_e32 v168, v8, v9
	v_add_u32_e32 v169, v16, v17
	v_add_u32_e32 v170, v15, v18
	v_add_u32_e32 v171, v20, v19
	v_lshlrev_b64 v[130:131], 1, v[2:3]
	v_add_u32_e32 v174, v22, v19
	s_branch .LBB0_283
